# on top of v135: DA loop slot 3 runs its 8 PV MFMAs first and the next tile's 4 QK MFMAs last (their K fragments get 8+ MFMA gaps of LDS latency cover)
# baseline (speedup 1.0000x reference)
.Lda_nocflip:
	ds_read_b128 v[210:213], v236 offset:0
	ds_read_b128 v[214:217], v236 offset:32
	ds_read_b128 v[218:221], v236 offset:64
	ds_read_b128 v[222:225], v236 offset:96
	v_mfma_f32_32x32x16_bf16 v[48:63], v[226:229], v[194:197], v[48:63]
	ds_read_b128 v[226:229], v235 offset:18464
	v_sub_f32_e32 v98, v98, v241
	v_sub_f32_e32 v99, v99, v241
	v_sub_f32_e32 v100, v100, v241
	v_sub_f32_e32 v101, v101, v241
	v_exp_f32_e32 v98, v98
	v_mfma_f32_32x32x16_bf16 v[32:47], v[230:233], v[194:197], v[32:47]
	ds_read_b128 v[230:233], v235 offset:23072
	v_exp_f32_e32 v99, v99
	v_exp_f32_e32 v100, v100
	v_exp_f32_e32 v101, v101
	v_mfma_f32_32x32x16_bf16 v[16:31], v[174:177], v[194:197], v[16:31]
	ds_read_b128 v[174:177], v235 offset:27680
	v_add_f32_e32 v191, v191, v98
	v_add_f32_e32 v192, v192, v99
	v_cvt_pk_bf16_f32 v202, v98, v99
	v_add_f32_e32 v191, v191, v100
	v_add_f32_e32 v192, v192, v101
	v_cvt_pk_bf16_f32 v203, v100, v101
	v_mfma_f32_32x32x16_bf16 v[0:15], v[246:249], v[194:197], v[0:15]
	ds_read_b128 v[246:249], v235 offset:32288
	v_sub_f32_e32 v102, v102, v241
	v_sub_f32_e32 v103, v103, v241
	v_sub_f32_e32 v104, v104, v241
	v_sub_f32_e32 v105, v105, v241
	v_exp_f32_e32 v102, v102
	s_waitcnt lgkmcnt(3)
	v_mfma_f32_32x32x16_bf16 v[48:63], v[226:229], v[198:201], v[48:63]
	ds_read_b128 v[226:229], v235 offset:18496
	v_exp_f32_e32 v103, v103
	v_exp_f32_e32 v104, v104
	v_exp_f32_e32 v105, v105
	s_waitcnt lgkmcnt(3)
	v_mfma_f32_32x32x16_bf16 v[32:47], v[230:233], v[198:201], v[32:47]
	ds_read_b128 v[230:233], v235 offset:23104
	v_add_f32_e32 v191, v191, v102
	v_add_f32_e32 v192, v192, v103
	v_cvt_pk_bf16_f32 v204, v102, v103
	v_add_f32_e32 v191, v191, v104
	v_add_f32_e32 v192, v192, v105
	v_cvt_pk_bf16_f32 v205, v104, v105
	s_waitcnt lgkmcnt(3)
	v_mfma_f32_32x32x16_bf16 v[16:31], v[174:177], v[198:201], v[16:31]
	ds_read_b128 v[174:177], v235 offset:27712
	v_sub_f32_e32 v106, v106, v241
	v_sub_f32_e32 v107, v107, v241
	v_sub_f32_e32 v108, v108, v241
	v_sub_f32_e32 v109, v109, v241
	v_exp_f32_e32 v106, v106
	s_waitcnt lgkmcnt(3)
	v_mfma_f32_32x32x16_bf16 v[0:15], v[246:249], v[198:201], v[0:15]
	ds_read_b128 v[246:249], v235 offset:32320
	v_exp_f32_e32 v107, v107
	v_exp_f32_e32 v108, v108
	v_exp_f32_e32 v109, v109
	v_mfma_f32_32x32x16_bf16 v[82:97], v[210:213], v[114:117], v[66:81]
	ds_read_b128 v[210:213], v236 offset:8704
	v_add_f32_e32 v191, v191, v106
	v_add_f32_e32 v192, v192, v107
	v_cvt_pk_bf16_f32 v206, v106, v107
	v_add_f32_e32 v191, v191, v108
	v_add_f32_e32 v192, v192, v109
	v_cvt_pk_bf16_f32 v207, v108, v109
	v_mfma_f32_32x32x16_bf16 v[82:97], v[214:217], v[118:121], v[82:97]
	ds_read_b128 v[214:217], v236 offset:8736
	v_sub_f32_e32 v110, v110, v241
	v_sub_f32_e32 v111, v111, v241
	v_sub_f32_e32 v112, v112, v241
	v_sub_f32_e32 v113, v113, v241
	v_exp_f32_e32 v110, v110
	v_mfma_f32_32x32x16_bf16 v[82:97], v[218:221], v[122:125], v[82:97]
	ds_read_b128 v[218:221], v236 offset:8768
	v_exp_f32_e32 v111, v111
	v_exp_f32_e32 v112, v112
	v_exp_f32_e32 v113, v113
	v_mfma_f32_32x32x16_bf16 v[82:97], v[222:225], v[126:129], v[82:97]
	ds_read_b128 v[222:225], v236 offset:8800
	v_add_f32_e32 v191, v191, v110
	v_add_f32_e32 v192, v192, v111
	v_cvt_pk_bf16_f32 v208, v110, v111
	v_add_f32_e32 v191, v191, v112
	v_add_f32_e32 v192, v192, v113
	v_cvt_pk_bf16_f32 v209, v112, v113
	s_add_i32 s4, s4, 1
	s_cmp_lt_u32 s4, 16
	s_waitcnt lgkmcnt(0)
	s_cbranch_scc1 .Lda_top
	v_mfma_f32_32x32x16_bf16 v[48:63], v[226:229], v[202:205], v[48:63]
	ds_read_b128 v[226:229], v235 offset:18528
	v_mfma_f32_32x32x16_bf16 v[32:47], v[230:233], v[202:205], v[32:47]
	ds_read_b128 v[230:233], v235 offset:23136
	v_mfma_f32_32x32x16_bf16 v[16:31], v[174:177], v[202:205], v[16:31]
	ds_read_b128 v[174:177], v235 offset:27744
	v_mfma_f32_32x32x16_bf16 v[0:15], v[246:249], v[202:205], v[0:15]
	ds_read_b128 v[246:249], v235 offset:32352
	s_waitcnt lgkmcnt(3)
	v_mfma_f32_32x32x16_bf16 v[48:63], v[226:229], v[206:209], v[48:63]
	s_waitcnt lgkmcnt(2)
	v_mfma_f32_32x32x16_bf16 v[32:47], v[230:233], v[206:209], v[32:47]
	s_waitcnt lgkmcnt(1)
	v_mfma_f32_32x32x16_bf16 v[16:31], v[174:177], v[206:209], v[16:31]
	s_waitcnt lgkmcnt(0)
	v_mfma_f32_32x32x16_bf16 v[0:15], v[246:249], v[206:209], v[0:15]
	v_add_f32_e32 v191, v191, v192
	s_nop 7
	s_nop 3
	v_add_f32_e32 v193, v193, v191
